# full attention unit: the two serialized QK K-fragment read->wait->MFMA chains (6+9 steps) software-pipelined two reads ahead over three fragment buffers (v[232:239] extra), counted lgkmcnt waits
# speedup vs baseline: 1.0066x; 1.0051x over previous
; #define LAS __attribute__((address_space(3)))
; __device__ __forceinline__ void attn_unit(LAS unsigned char* lds, int unit, int mode, const bf16* QKVG, const float* sinks, const float* gain_a, bf16* MIX, float* SSA) {
;     ...
;     for (int i = i0; i < i1; ++i) {
;         const int inx = (i < 3) ? (i + 1) : 3;
; #pragma unroll
;         for (int k = 0; k < 4; ++k) qrow[k] = __builtin_nontemporal_load((const v4u*)(qrow0 + (size_t)(32 * inx + 8 * k) * QP));
; #pragma unroll
;         for (int k = 0; k < 4; ++k) grow[k] = __builtin_nontemporal_load((const v4u*)(grow0 + (size_t)(32 * i + 8 * k) * QP));
;         int qq = q - 4 * hh; asm volatile("" : "+v"(qq));
;         float base = slope2 * (float)(4 * hh); asm volatile("" : "+v"(base));
;         f32x16 st[5];
; #pragma unroll
;         for (int j = 0; j < 5; ++j) {
;             const bool tile_ok = !(nblk == 0 && (i + j) < 4);
;             const float sl = tile_ok ? slope2 : 0.f, bs = tile_ok ? base : -INFINITY;
; #pragma unroll
;             for (int r = 0; r < 16; ++r) st[j][r] = fmaf(sl, (float)((r & 3) + 8 * (r >> 2) + 32 * j), bs);
;         }
;         {
;             const LAS bf16* kp = Ks + (32 * i + q) * KP + hh * 8;
;             bf16x8 kf[2][5];
; #pragma unroll
;             for (int j = 0; j < 5; ++j) kf[0][j] = *(const LAS bf16x8*)(kp + j * 32 * KP);
; #pragma unroll
;             for (int s = 0; s < 4; ++s) {
;                 if (s < 3) {
; #pragma unroll
;                     for (int j = 0; j < 5; ++j) kf[(s + 1) & 1][j] = *(const LAS bf16x8*)(kp + j * 32 * KP + 16 * (s + 1));
;                 }
; #pragma unroll
;                 for (int j = 0; j < 5; ++j) st[j] = __builtin_amdgcn_mfma_f32_32x32x16_bf16(kf[s & 1][j], qr[s], st[j], 0, 0, 0);
;             }
.LBB0_296:
	s_waitcnt lgkmcnt(4)
	v_lshl_add_u64 v[0:1], v[112:113], 0, s[88:89]
	s_mov_b32 s6, 0x7800000
	v_add_co_u32_e64 v2, s[6:7], s6, v0
	s_cmp_lt_u32 s1, 3
	s_nop 0
	v_addc_co_u32_e64 v3, s[6:7], 0, v1, s[6:7]
	s_mov_b32 s6, 0x7809000
	s_nop 0
	v_add_co_u32_e64 v4, s[6:7], s6, v0
	s_cselect_b32 s94, s0, 0x60
	s_nop 0
	v_addc_co_u32_e64 v5, s[6:7], 0, v1, s[6:7]
	s_mov_b32 s6, 0x7812000
	s_nop 0
	v_add_co_u32_e64 v6, s[6:7], s6, v0
	v_mov_b32_e32 v152, v141
	s_nop 0
	v_addc_co_u32_e64 v7, s[6:7], 0, v1, s[6:7]
	s_mov_b32 s6, 0x781b000
	s_nop 0
	v_add_co_u32_e64 v0, s[6:7], s6, v0
	v_mov_b32_e32 v38, v142
	s_nop 0
	v_addc_co_u32_e64 v1, s[6:7], 0, v1, s[6:7]
	s_or_b32 s6, s94, 8
	s_nop 0
	v_mad_u64_u32 v[8:9], s[6:7], s6, v150, v[100:101]
	s_or_b32 s6, s94, 16
	s_nop 0
	v_mad_u64_u32 v[10:11], s[6:7], s6, v150, v[100:101]
	v_mad_u64_u32 v[12:13], s[6:7], s94, v150, v[100:101]
	s_or_b32 s6, s94, 24
	s_nop 0
	v_mad_u64_u32 v[14:15], s[6:7], s6, v150, v[100:101]
	ds_read_b128 v[82:85], v139 offset:96
	ds_read_b128 v[86:89], v139 offset:64
	ds_read_b128 v[94:97], v139
	ds_read_b128 v[90:93], v139 offset:32
	global_load_dwordx4 v[48:51], v[12:13], off nt
	global_load_dwordx4 v[52:55], v[8:9], off nt
	global_load_dwordx4 v[56:59], v[10:11], off nt
	global_load_dwordx4 v[60:63], v[14:15], off nt
	global_load_dwordx4 v[64:67], v[2:3], off offset:2560 nt
	global_load_dwordx4 v[68:71], v[4:5], off offset:2560 nt
	global_load_dwordx4 v[72:75], v[6:7], off offset:2560 nt
	global_load_dwordx4 v[76:79], v[0:1], off offset:2560 nt
	ds_read_b128 v[16:19], v145
	ds_read_b128 v[198:201], v145 offset:13824
	ds_read_b128 v[34:37], v145 offset:18432
	ds_read_b128 v[232:235], v145 offset:32
	ds_read_b128 v[236:239], v145 offset:18464
	v_cndmask_b32_e32 v14, v151, v38, vcc
	v_fma_f32 v0, 0, v106, v14
	v_add_f32_e32 v1, v106, v14
	v_pk_fma_f32 v[2:3], v[106:107], s[10:11], v[14:15] op_sel_hi:[1,1,0]
	v_pk_fma_f32 v[4:5], v[106:107], s[12:13], v[14:15] op_sel_hi:[1,1,0]
	v_pk_fma_f32 v[6:7], v[106:107], s[14:15], v[14:15] op_sel_hi:[1,1,0]
	v_pk_fma_f32 v[8:9], v[106:107], s[16:17], v[14:15] op_sel_hi:[1,1,0]
	v_pk_fma_f32 v[10:11], v[106:107], s[18:19], v[14:15] op_sel_hi:[1,1,0]
	v_pk_fma_f32 v[12:13], v[106:107], s[20:21], v[14:15] op_sel_hi:[1,1,0]
	v_pk_fma_f32 v[14:15], v[106:107], s[22:23], v[14:15] op_sel_hi:[1,1,0]
	v_mov_b32_e32 v105, v104
	v_pk_fma_f32 v[30:31], v[104:105], s[72:73], v[38:39] op_sel_hi:[1,1,0]
	s_waitcnt lgkmcnt(4)
	v_mfma_f32_32x32x16_bf16 v[0:15], v[16:19], v[94:97], v[0:15]
	v_fma_f32 v28, v104, s74, v38
	v_fma_f32 v29, v105, s75, v38
	v_fma_f32 v26, v104, s76, v38
	v_fma_f32 v27, v105, s77, v38
	v_fma_f32 v24, v104, s78, v38
	v_fma_f32 v25, v105, s79, v38
	v_pk_fma_f32 v[22:23], v[104:105], s[80:81], v[38:39] op_sel_hi:[1,1,0]
	v_pk_fma_f32 v[20:21], v[104:105], s[82:83], v[38:39] op_sel_hi:[1,1,0]
	v_pk_fma_f32 v[18:19], v[104:105], s[84:85], v[38:39] op_sel_hi:[1,1,0]
	v_pk_fma_f32 v[16:17], v[108:109], s[86:87], v[38:39] op_sel_hi:[1,1,0]
	s_cmp_gt_u32 s1, 2
	s_cselect_b64 s[6:7], -1, 0
	s_waitcnt lgkmcnt(2)
	v_mfma_f32_32x32x16_bf16 v[16:31], v[34:37], v[94:97], v[16:31]
	ds_read_b128 v[34:37], v145 offset:64
	s_or_b64 s[6:7], vcc, s[6:7]
	s_cmp_gt_u32 s1, 1
	v_cndmask_b32_e64 v32, 0, v104, s[6:7]
	v_cndmask_b32_e64 v132, v151, v38, s[6:7]
	s_cselect_b64 s[6:7], -1, 0
	s_or_b64 s[6:7], vcc, s[6:7]
	s_waitcnt lgkmcnt(2)
	v_mfma_f32_32x32x16_bf16 v[0:15], v[232:235], v[90:93], v[0:15]
	ds_read_b128 v[232:235], v145 offset:18496
	v_cndmask_b32_e64 v126, 0, v104, s[6:7]
	v_cndmask_b32_e64 v128, v151, v38, s[6:7]
	s_or_b32 s6, s1, s93
	s_cmp_eq_u32 s6, 0
	s_cselect_b64 s[6:7], -1, 0
	v_cndmask_b32_e64 v122, v104, 0, s[6:7]
	s_waitcnt lgkmcnt(2)
	v_mfma_f32_32x32x16_bf16 v[16:31], v[236:239], v[90:93], v[16:31]
	ds_read_b128 v[236:239], v145 offset:96
	v_cndmask_b32_e64 v124, v38, v151, s[6:7]
	v_cmp_gt_i32_e64 s[6:7], 0, v152
	v_fma_f32 v46, v32, s24, v132
	v_fma_f32 v47, v32, s25, v132
	v_pk_fma_f32 v[44:45], v[32:33], s[26:27], v[132:133] op_sel_hi:[0,1,0]
	v_pk_fma_f32 v[42:43], v[32:33], s[28:29], v[132:133] op_sel_hi:[0,1,0]
	v_pk_fma_f32 v[40:41], v[32:33], s[30:31], v[132:133] op_sel_hi:[0,1,0]
	s_waitcnt lgkmcnt(2)
	v_mfma_f32_32x32x16_bf16 v[0:15], v[34:37], v[86:89], v[0:15]
	ds_read_b128 v[34:37], v145 offset:18528
	v_fma_f32 v38, v32, s34, v132
	v_fma_f32 v39, v32, s35, v132
	s_waitcnt lgkmcnt(2)
	v_mfma_f32_32x32x16_bf16 v[16:31], v[232:235], v[86:89], v[16:31]
	s_waitcnt lgkmcnt(1)
	v_mfma_f32_32x32x16_bf16 v[0:15], v[236:239], v[82:85], v[0:15]
	s_waitcnt lgkmcnt(0)
; #define LAS __attribute__((address_space(3)))
; __device__ __forceinline__ void attn_unit(LAS unsigned char* lds, int unit, int mode, const bf16* QKVG, const float* sinks, const float* gain_a, bf16* MIX, float* SSA) {
;     ...
;         {
;             const LAS bf16* kp = Ks + (32 * i + q) * KP + hh * 8;
;             bf16x8 kf[2][5];
; #pragma unroll
;             for (int j = 0; j < 5; ++j) kf[0][j] = *(const LAS bf16x8*)(kp + j * 32 * KP);
; #pragma unroll
;             for (int s = 0; s < 4; ++s) {
;                 if (s < 3) {
; #pragma unroll
;                     for (int j = 0; j < 5; ++j) kf[(s + 1) & 1][j] = *(const LAS bf16x8*)(kp + j * 32 * KP + 16 * (s + 1));
;                 }
; #pragma unroll
;                 for (int j = 0; j < 5; ++j) st[j] = __builtin_amdgcn_mfma_f32_32x32x16_bf16(kf[s & 1][j], qr[s], st[j], 0, 0, 0);
;             }
;         }
;         const float sinkq = fmaf(slope2, (float)(128 + 4 * hh) + (float)qq, sink2);
;         float mx = sinkq;
; #pragma unroll
;         for (int r = 0; r < 16; ++r) {
;             const int cr = (r & 3) + 8 * (r >> 2);
;             const bool up = cr > qq;
;             st[0][r] = up ? st[0][r] : -INFINITY;
;             st[4][r] = up ? -INFINITY : st[4][r];
;         }
	v_mfma_f32_32x32x16_bf16 v[16:31], v[34:37], v[82:85], v[16:31]
	s_nop 8
	v_cndmask_b32_e64 v180, v151, v0, s[6:7]
	v_xor_b32_e32 v0, 32, v147
	v_fma_f32 v36, v32, s36, v132
	v_fma_f32 v37, v32, s37, v132
	v_fma_f32 v34, v32, s38, v132
	v_fma_f32 v35, v32, s39, v132
	v_pk_fma_f32 v[32:33], v[32:33], s[40:41], v[132:133] op_sel_hi:[0,1,0]
	v_cndmask_b32_e64 v179, v16, v151, s[6:7]
	v_cmp_gt_i32_e64 s[6:7], 1, v152
	s_nop 1
	v_cndmask_b32_e64 v184, v151, v1, s[6:7]
	v_cndmask_b32_e64 v175, v17, v151, s[6:7]
	v_cmp_gt_i32_e64 s[6:7], 2, v152
	v_and_b32_e32 v1, 64, v147
	v_add_u32_e32 v1, 64, v1
	v_cndmask_b32_e64 v188, v151, v2, s[6:7]
	v_cndmask_b32_e64 v176, v18, v151, s[6:7]
	v_cmp_gt_i32_e64 s[6:7], 3, v152
	v_pk_fma_f32 v[16:17], v[126:127], s[2:3], v[128:129] op_sel_hi:[0,1,0]
	s_nop 0
	v_cndmask_b32_e64 v192, v151, v3, s[6:7]
	v_cndmask_b32_e64 v178, v19, v151, s[6:7]
	v_cmp_gt_i32_e64 s[6:7], 8, v152
	v_pk_fma_f32 v[18:19], v[126:127], s[54:55], v[128:129] op_sel_hi:[0,1,0]
	s_nop 0
	v_cndmask_b32_e64 v181, v151, v4, s[6:7]
	v_cndmask_b32_e64 v177, v20, v151, s[6:7]
	v_cmp_gt_i32_e64 s[6:7], 9, v152
	s_nop 1
	v_cndmask_b32_e64 v185, v151, v5, s[6:7]
	v_cndmask_b32_e64 v174, v21, v151, s[6:7]
	v_cmp_gt_i32_e64 s[6:7], 10, v152
	v_pk_fma_f32 v[20:21], v[126:127], s[52:53], v[128:129] op_sel_hi:[0,1,0]
	s_nop 0
	v_cndmask_b32_e64 v189, v151, v6, s[6:7]
	v_cndmask_b32_e64 v173, v22, v151, s[6:7]
	v_cmp_gt_i32_e64 s[6:7], 11, v152
	s_nop 1
	v_cndmask_b32_e64 v193, v151, v7, s[6:7]
	v_cndmask_b32_e64 v158, v23, v151, s[6:7]
	v_cmp_gt_i32_e64 s[6:7], 16, v152
	ds_read_b128 v[4:7], v145 offset:9216
	v_pk_fma_f32 v[22:23], v[126:127], s[50:51], v[128:129] op_sel_hi:[0,1,0]
	v_cndmask_b32_e64 v182, v151, v8, s[6:7]
	v_cndmask_b32_e64 v172, v24, v151, s[6:7]
	v_cmp_gt_i32_e64 s[6:7], 17, v152
	s_nop 1
	v_cndmask_b32_e64 v186, v151, v9, s[6:7]
	v_cndmask_b32_e64 v159, v25, v151, s[6:7]
	v_cmp_gt_i32_e64 s[6:7], 18, v152
	v_pk_fma_f32 v[24:25], v[126:127], s[48:49], v[128:129] op_sel_hi:[0,1,0]
	v_pk_fma_f32 v[8:9], v[122:123], s[62:63], v[124:125] op_sel_hi:[0,1,0]
	v_cndmask_b32_e64 v190, v151, v10, s[6:7]
	v_cndmask_b32_e64 v157, v26, v151, s[6:7]
	v_cmp_gt_i32_e64 s[6:7], 19, v152
	s_nop 1
	v_cndmask_b32_e64 v194, v151, v11, s[6:7]
	v_cndmask_b32_e64 v156, v27, v151, s[6:7]
	v_cmp_gt_i32_e64 s[6:7], 24, v152
	v_pk_fma_f32 v[26:27], v[126:127], s[46:47], v[128:129] op_sel_hi:[0,1,0]
	v_pk_fma_f32 v[10:11], v[122:123], s[60:61], v[124:125] op_sel_hi:[0,1,0]
	v_cndmask_b32_e64 v183, v151, v12, s[6:7]
	v_cndmask_b32_e64 v105, v28, v151, s[6:7]
	v_cmp_gt_i32_e64 s[6:7], 25, v152
	s_nop 1
	v_cndmask_b32_e64 v187, v151, v13, s[6:7]
	v_cndmask_b32_e64 v153, v29, v151, s[6:7]
	v_cmp_gt_i32_e64 s[6:7], 26, v152
	v_pk_fma_f32 v[28:29], v[126:127], s[44:45], v[128:129] op_sel_hi:[0,1,0]
	v_pk_fma_f32 v[12:13], v[122:123], s[58:59], v[124:125] op_sel_hi:[0,1,0]
	v_cndmask_b32_e64 v191, v151, v14, s[6:7]
	v_cndmask_b32_e64 v155, v30, v151, s[6:7]
	v_cmp_gt_i32_e64 s[6:7], 27, v152
	s_nop 1
	v_cndmask_b32_e64 v195, v151, v15, s[6:7]
	v_cndmask_b32_e64 v154, v31, v151, s[6:7]
	v_cmp_lt_i32_e64 s[6:7], v0, v1
	v_pk_fma_f32 v[30:31], v[126:127], s[42:43], v[128:129] op_sel_hi:[0,1,0]
	v_pk_fma_f32 v[14:15], v[122:123], s[56:57], v[124:125] op_sel_hi:[0,1,0]
	v_cndmask_b32_e64 v196, v147, v0, s[6:7]
	v_add_u32_e32 v0, s0, v133
	v_subrev_u32_e32 v0, 32, v0
	v_ashrrev_i32_e32 v1, 31, v0
	v_lshlrev_b64 v[0:1], 12, v[0:1]
	v_lshl_add_u64 v[114:115], v[110:111], 0, v[0:1]
	ds_read_b128 v[0:3], v145 offset:4608
	s_waitcnt lgkmcnt(0)
	v_mfma_f32_32x32x16_bf16 v[32:47], v[0:3], v[94:97], v[32:47]
	v_fma_f32 v2, v122, s68, v124
	v_fma_f32 v3, v122, s69, v124
	v_fma_f32 v0, v122, s70, v124
	v_fma_f32 v1, v122, s71, v124
	s_mov_b32 s6, 0x8000
	v_add_co_u32_e64 v116, s[6:7], s6, v114
	s_nop 1
	v_addc_co_u32_e64 v117, s[6:7], 0, v115, s[6:7]
	v_mfma_f32_32x32x16_bf16 v[16:31], v[4:7], v[94:97], v[16:31]
	v_fma_f32 v6, v122, s64, v124
	v_fma_f32 v7, v122, s65, v124
	v_fma_f32 v4, v122, s66, v124
	v_fma_f32 v5, v122, s67, v124
	s_mov_b32 s6, 0x10000
	v_add_co_u32_e64 v118, s[6:7], s6, v114
	s_nop 1
	v_addc_co_u32_e64 v119, s[6:7], 0, v115, s[6:7]
	v_mfma_f32_32x32x16_bf16 v[0:15], v[198:201], v[94:97], v[0:15]
	ds_read_b128 v[94:97], v145 offset:4640
	ds_read_b128 v[232:235], v145 offset:9248
	ds_read_b128 v[236:239], v145 offset:13856
	s_mov_b32 s6, 0x18000
	v_add_co_u32_e64 v120, s[6:7], s6, v114
	s_nop 1
	v_addc_co_u32_e64 v121, s[6:7], 0, v115, s[6:7]
	s_waitcnt lgkmcnt(2)
	v_mfma_f32_32x32x16_bf16 v[32:47], v[94:97], v[90:93], v[32:47]
	ds_read_b128 v[94:97], v145 offset:4672
	s_waitcnt lgkmcnt(2)
	v_mfma_f32_32x32x16_bf16 v[16:31], v[232:235], v[90:93], v[16:31]
	ds_read_b128 v[232:235], v145 offset:9280
	s_waitcnt lgkmcnt(2)
	v_mfma_f32_32x32x16_bf16 v[0:15], v[236:239], v[90:93], v[0:15]
	ds_read_b128 v[236:239], v145 offset:13888
	s_waitcnt lgkmcnt(2)
	v_mfma_f32_32x32x16_bf16 v[32:47], v[94:97], v[86:89], v[32:47]
	ds_read_b128 v[94:97], v145 offset:4704
	s_waitcnt lgkmcnt(2)
	v_mfma_f32_32x32x16_bf16 v[16:31], v[232:235], v[86:89], v[16:31]
	ds_read_b128 v[232:235], v145 offset:9312
	s_waitcnt lgkmcnt(2)
	v_mfma_f32_32x32x16_bf16 v[0:15], v[236:239], v[86:89], v[0:15]
	ds_read_b128 v[236:239], v145 offset:13920
	v_cvt_f32_i32_e32 v90, v152
	v_add_f32_e32 v90, v143, v90
	s_waitcnt lgkmcnt(2)
	v_mfma_f32_32x32x16_bf16 v[32:47], v[94:97], v[82:85], v[32:47]
	s_waitcnt lgkmcnt(1)
	v_mfma_f32_32x32x16_bf16 v[16:31], v[232:235], v[82:85], v[16:31]
	s_waitcnt lgkmcnt(0)
; __device__ __forceinline__ void attn_unit(LAS unsigned char* lds, int unit, int mode, const bf16* QKVG, const float* sinks, const float* gain_a, bf16* MIX, float* SSA) {
;     ...
;                 for (int j = 0; j < 5; ++j) st[j] = __builtin_amdgcn_mfma_f32_32x32x16_bf16(kf[s & 1][j], qr[s], st[j], 0, 0, 0);
;             }
;         }
;         const float sinkq = fmaf(slope2, (float)(128 + 4 * hh) + (float)qq, sink2);
;         float mx = sinkq;
; #pragma unroll
;         for (int r = 0; r < 16; ++r) {
;             const int cr = (r & 3) + 8 * (r >> 2);
;             const bool up = cr > qq;
;             st[0][r] = up ? st[0][r] : -INFINITY;
;             st[4][r] = up ? -INFINITY : st[4][r];
;         }
; #pragma unroll
;         for (int j = 0; j < 5; ++j)
; #pragma unroll
;             for (int r = 0; r < 16; ++r) mx = fmaxf(mx, st[j][r]);
;         mx = fmaxf(mx, __shfl_xor(mx, 32));
;         float sum = 0.f;
; #pragma unroll
;         for (int j = 0; j < 5; ++j)
; #pragma unroll
;             for (int r = 0; r < 16; ++r) { const float p = __builtin_amdgcn_exp2f(st[j][r] - mx); st[j][r] = p; sum += p; }
;         sum += __shfl_xor(sum, 32);
;         sum += __builtin_amdgcn_exp2f(sinkq - mx);
	v_mfma_f32_32x32x16_bf16 v[0:15], v[236:239], v[82:85], v[0:15]
	v_fma_f32 v83, v104, v90, v140
	v_max3_f32 v82, v83, v180, v184
	v_max3_f32 v82, v82, v188, v192
	v_max3_f32 v82, v82, v181, v185
	v_max3_f32 v82, v82, v189, v193
	v_max3_f32 v82, v82, v182, v186
	v_max3_f32 v82, v82, v190, v194
	v_max3_f32 v82, v82, v183, v187
	v_max3_f32 v82, v82, v191, v195
	v_max3_f32 v82, v82, v32, v33
	v_max3_f32 v82, v82, v34, v35
	v_max3_f32 v82, v82, v36, v37
	v_max3_f32 v82, v82, v38, v39
	v_max3_f32 v82, v82, v40, v41
	v_max3_f32 v82, v82, v42, v43
	v_max3_f32 v82, v82, v44, v45
	v_max3_f32 v82, v82, v46, v47
	v_max3_f32 v82, v82, v16, v17
	v_max3_f32 v82, v82, v18, v19
	v_max3_f32 v82, v82, v20, v21
	v_max3_f32 v82, v82, v22, v23
	v_max3_f32 v82, v82, v24, v25
	v_max3_f32 v82, v82, v26, v27
	v_max3_f32 v82, v82, v28, v29
	v_max3_f32 v82, v82, v30, v31
	v_max3_f32 v82, v82, v0, v1
	v_max3_f32 v82, v82, v2, v3
	v_max3_f32 v82, v82, v4, v5
	v_max3_f32 v82, v82, v6, v7
	v_max3_f32 v82, v82, v8, v9
	v_max3_f32 v82, v82, v10, v11
	v_max3_f32 v82, v82, v12, v13
	v_max3_f32 v82, v82, v14, v15
	v_max3_f32 v82, v82, v179, v175
	v_max3_f32 v82, v82, v176, v178
	v_max3_f32 v82, v82, v177, v174
	v_max3_f32 v82, v82, v173, v158
	v_max3_f32 v82, v82, v172, v159
	v_max3_f32 v82, v82, v157, v156
	v_max3_f32 v82, v82, v105, v153
	v_max3_f32 v84, v82, v155, v154
	v_lshlrev_b32_e32 v82, 2, v196
	ds_bpermute_b32 v85, v82, v84
	s_waitcnt lgkmcnt(0)
	v_max_f32_e32 v85, v85, v85
	v_max_f32_e32 v92, v84, v85
	v_sub_f32_e32 v84, v180, v92
	v_exp_f32_e32 v84, v84
	v_sub_f32_e32 v85, v184, v92
	v_exp_f32_e32 v85, v85
	v_sub_f32_e32 v86, v188, v92
	v_exp_f32_e32 v86, v86
	v_sub_f32_e32 v87, v192, v92
	v_exp_f32_e32 v87, v87
	v_sub_f32_e32 v89, v181, v92
	v_add_f32_e32 v88, 0, v84
	v_exp_f32_e32 v89, v89
	v_sub_f32_e32 v90, v185, v92
	v_add_f32_e32 v88, v85, v88
	v_exp_f32_e32 v90, v90
	v_sub_f32_e32 v91, v189, v92
	v_add_f32_e32 v88, v86, v88
	v_exp_f32_e32 v91, v91
	v_sub_f32_e32 v93, v193, v92
	v_add_f32_e32 v88, v87, v88
	v_exp_f32_e32 v93, v93
	v_sub_f32_e32 v94, v182, v92
	v_add_f32_e32 v88, v89, v88
	v_exp_f32_e32 v94, v94
	v_sub_f32_e32 v95, v186, v92
	v_add_f32_e32 v88, v90, v88
	v_exp_f32_e32 v95, v95
	v_sub_f32_e32 v96, v190, v92
	v_add_f32_e32 v88, v91, v88
	v_exp_f32_e32 v96, v96
	v_sub_f32_e32 v97, v194, v92
	v_add_f32_e32 v88, v93, v88
	v_exp_f32_e32 v97, v97
	v_sub_f32_e32 v122, v183, v92
	v_add_f32_e32 v88, v94, v88
	v_exp_f32_e32 v122, v122
	v_sub_f32_e32 v124, v187, v92
	v_add_f32_e32 v88, v95, v88
	v_exp_f32_e32 v124, v124
	v_sub_f32_e32 v126, v191, v92
	v_add_f32_e32 v88, v96, v88
	v_exp_f32_e32 v126, v126
	v_sub_f32_e32 v128, v195, v92
	v_add_f32_e32 v88, v97, v88
	v_exp_f32_e32 v128, v128
	v_sub_f32_e32 v32, v32, v92
	v_add_f32_e32 v88, v122, v88
	v_exp_f32_e32 v132, v32
	v_sub_f32_e32 v32, v33, v92
	v_add_f32_e32 v88, v124, v88
	v_exp_f32_e32 v152, v32
	v_sub_f32_e32 v32, v34, v92
	v_add_f32_e32 v88, v126, v88
	v_exp_f32_e32 v180, v32
	v_sub_f32_e32 v32, v35, v92
	v_add_f32_e32 v88, v128, v88
	v_exp_f32_e32 v181, v32
	v_sub_f32_e32 v33, v36, v92
	v_add_f32_e32 v32, v132, v88
	v_exp_f32_e32 v182, v33
	v_sub_f32_e32 v33, v37, v92
	v_add_f32_e32 v32, v152, v32
	v_exp_f32_e32 v183, v33
	v_sub_f32_e32 v33, v38, v92
	v_add_f32_e32 v32, v180, v32
	v_exp_f32_e32 v184, v33
	v_sub_f32_e32 v33, v39, v92
	v_add_f32_e32 v32, v181, v32
	v_exp_f32_e32 v185, v33
	v_sub_f32_e32 v33, v40, v92
	v_add_f32_e32 v32, v182, v32
	v_exp_f32_e32 v186, v33
	v_sub_f32_e32 v33, v41, v92
	v_add_f32_e32 v32, v183, v32
	v_exp_f32_e32 v187, v33
	v_sub_f32_e32 v33, v42, v92
	v_add_f32_e32 v32, v184, v32
	v_exp_f32_e32 v188, v33
	v_sub_f32_e32 v33, v43, v92
	v_add_f32_e32 v32, v185, v32
	v_exp_f32_e32 v189, v33
	v_sub_f32_e32 v33, v44, v92
	v_add_f32_e32 v32, v186, v32
	v_exp_f32_e32 v190, v33
	v_sub_f32_e32 v33, v45, v92
	v_add_f32_e32 v32, v187, v32
	v_exp_f32_e32 v191, v33
	v_sub_f32_e32 v33, v46, v92
	v_add_f32_e32 v32, v188, v32
	v_exp_f32_e32 v192, v33
	v_sub_f32_e32 v33, v47, v92
	v_add_f32_e32 v32, v189, v32
	v_exp_f32_e32 v193, v33
	v_sub_f32_e32 v16, v16, v92
	v_add_f32_e32 v32, v190, v32
	v_exp_f32_e32 v194, v16
	v_sub_f32_e32 v16, v17, v92
	v_add_f32_e32 v32, v191, v32
	v_exp_f32_e32 v195, v16
	v_sub_f32_e32 v16, v18, v92
	v_add_f32_e32 v32, v192, v32
	v_exp_f32_e32 v196, v16
	v_sub_f32_e32 v16, v19, v92
	v_add_f32_e32 v32, v193, v32
	v_exp_f32_e32 v197, v16
	v_sub_f32_e32 v17, v20, v92
	v_add_f32_e32 v16, v194, v32
	v_exp_f32_e32 v198, v17
	v_sub_f32_e32 v17, v21, v92
	v_add_f32_e32 v16, v195, v16
	v_exp_f32_e32 v199, v17
	v_sub_f32_e32 v17, v22, v92
	v_add_f32_e32 v16, v196, v16
	v_exp_f32_e32 v200, v17
	v_sub_f32_e32 v17, v23, v92
	v_add_f32_e32 v16, v197, v16
	v_exp_f32_e32 v201, v17
	v_sub_f32_e32 v17, v24, v92
	v_add_f32_e32 v16, v198, v16
	v_exp_f32_e32 v202, v17
	v_sub_f32_e32 v17, v25, v92
	v_add_f32_e32 v16, v199, v16
	v_exp_f32_e32 v203, v17
	v_sub_f32_e32 v17, v26, v92
	v_add_f32_e32 v16, v200, v16
	v_exp_f32_e32 v204, v17
	v_sub_f32_e32 v17, v27, v92
	v_add_f32_e32 v16, v201, v16
	v_exp_f32_e32 v205, v17
	v_sub_f32_e32 v17, v28, v92
	v_add_f32_e32 v16, v202, v16
	v_exp_f32_e32 v206, v17
	v_sub_f32_e32 v17, v29, v92
	v_add_f32_e32 v16, v203, v16
	v_exp_f32_e32 v207, v17
	v_sub_f32_e32 v17, v30, v92
	v_add_f32_e32 v16, v204, v16
	v_exp_f32_e32 v208, v17
	v_sub_f32_e32 v17, v31, v92
	v_add_f32_e32 v16, v205, v16
	v_exp_f32_e32 v209, v17
	v_sub_f32_e32 v0, v0, v92
	v_add_f32_e32 v16, v206, v16
	v_exp_f32_e32 v210, v0
	v_sub_f32_e32 v0, v1, v92
	v_add_f32_e32 v16, v207, v16
	v_exp_f32_e32 v211, v0
	v_sub_f32_e32 v0, v2, v92
	v_add_f32_e32 v16, v208, v16
	v_exp_f32_e32 v212, v0
	v_sub_f32_e32 v0, v3, v92
	v_add_f32_e32 v16, v209, v16
	v_exp_f32_e32 v213, v0
	v_add_f32_e32 v0, v210, v16
	v_add_f32_e32 v0, v211, v0
	v_add_f32_e32 v0, v212, v0
	v_add_f32_e32 v20, v213, v0
	v_sub_f32_e32 v0, v4, v92
	v_exp_f32_e32 v214, v0
	v_sub_f32_e32 v0, v5, v92
	v_exp_f32_e32 v215, v0
	v_sub_f32_e32 v0, v6, v92
	v_exp_f32_e32 v216, v0
	v_add_f32_e32 v4, v214, v20
	v_add_f32_e32 v4, v215, v4
	v_cvt_pk_bf16_f32 v0, v84, v85
	v_add_f32_e32 v20, v216, v4
	v_sub_f32_e32 v4, v7, v92
	v_cvt_pk_bf16_f32 v1, v86, v87
	v_cvt_pk_bf16_f32 v2, v89, v90
	v_cvt_pk_bf16_f32 v3, v91, v93
	v_exp_f32_e32 v93, v4
	v_sub_f32_e32 v4, v8, v92
	ds_read_b128 v[16:19], v99
	v_exp_f32_e32 v217, v4
	ds_read_b128 v[4:7], v99 offset:16896
	s_waitcnt lgkmcnt(1)
; #define LAS __attribute__((address_space(3)))
; __device__ __forceinline__ unsigned pk2(float lo, float hi) { return pg8::cvt_pk_bf16(lo, hi); }
; __device__ __forceinline__ void attn_unit(LAS unsigned char* lds, int unit, int mode, const bf16* QKVG, const float* sinks, const float* gain_a, bf16* MIX, float* SSA) {
;     ...
;         f32x16 ot[2]; ot[0] = f32x16{}; ot[1] = f32x16{};
; #pragma unroll
;         for (int j = 0; j < 5; ++j)
; #pragma unroll
;             for (int s2 = 0; s2 < 2; ++s2) {
;                 v4u pw; pw.x = pk2(st[j][8 * s2 + 0], st[j][8 * s2 + 1]); pw.y = pk2(st[j][8 * s2 + 2], st[j][8 * s2 + 3]);
;                 pw.z = pk2(st[j][8 * s2 + 4], st[j][8 * s2 + 5]); pw.w = pk2(st[j][8 * s2 + 6], st[j][8 * s2 + 7]);
;                 const bf16x8 pf = __builtin_bit_cast(bf16x8, pw);
; #pragma unroll
;                 for (int db = 0; db < 2; ++db) {
;                     const bf16x8 vf = *(const LAS bf16x8*)(Vt + (db * 32 + q) * VP + 32 * (i + j) + 16 * s2 + 8 * hh);
;                     ot[db] = __builtin_amdgcn_mfma_f32_32x32x16_bf16(vf, pf, ot[db], 0, 0, 0);
;                 }
;             }
;         float ss = 0.f;
; #pragma unroll
;         for (int k = 0; k < 4; ++k) *(LAS v4u*)(wt_row + 8 * k * KP) = grow[k];
	v_mfma_f32_32x32x16_bf16 v[32:47], v[16:19], v[0:3], 0
	v_add_f32_e32 v8, v93, v20
	v_cvt_pk_bf16_f32 v84, v94, v95
	v_cvt_pk_bf16_f32 v85, v96, v97
	v_cvt_pk_bf16_f32 v86, v122, v124
	v_cvt_pk_bf16_f32 v87, v126, v128
	ds_read_b128 v[88:91], v99 offset:32
	v_add_f32_e32 v218, v217, v8
	s_waitcnt lgkmcnt(1)
	v_mfma_f32_32x32x16_bf16 v[16:31], v[4:7], v[0:3], 0
	v_sub_f32_e32 v0, v9, v92
	v_exp_f32_e32 v94, v0
	v_sub_f32_e32 v0, v10, v92
	v_exp_f32_e32 v95, v0
	v_sub_f32_e32 v0, v11, v92
	v_exp_f32_e32 v96, v0
	ds_read_b128 v[0:3], v99 offset:16928
	v_sub_f32_e32 v4, v12, v92
	s_waitcnt lgkmcnt(1)
	v_mfma_f32_32x32x16_bf16 v[32:47], v[88:91], v[84:87], v[32:47]
	v_exp_f32_e32 v88, v4
	v_cvt_pk_bf16_f32 v4, v132, v152
	v_cvt_pk_bf16_f32 v5, v180, v181
	v_cvt_pk_bf16_f32 v6, v182, v183
	v_cvt_pk_bf16_f32 v7, v184, v185
	ds_read_b128 v[8:11], v99 offset:64
	s_waitcnt lgkmcnt(1)
	v_mfma_f32_32x32x16_bf16 v[16:31], v[0:3], v[84:87], v[16:31]
	v_add_f32_e32 v0, v94, v218
	v_add_f32_e32 v0, v95, v0
	v_add_f32_e32 v0, v96, v0
	v_add_f32_e32 v12, v88, v0
	v_sub_f32_e32 v0, v13, v92
	v_exp_f32_e32 v89, v0
	ds_read_b128 v[0:3], v99 offset:16960
	s_waitcnt lgkmcnt(1)
	v_mfma_f32_32x32x16_bf16 v[32:47], v[8:11], v[4:7], v[32:47]
	v_sub_f32_e32 v8, v14, v92
	v_exp_f32_e32 v90, v8
	v_cvt_pk_bf16_f32 v8, v186, v187
	v_cvt_pk_bf16_f32 v9, v188, v189
	v_cvt_pk_bf16_f32 v10, v190, v191
	v_cvt_pk_bf16_f32 v11, v192, v193
	ds_read_b128 v[84:87], v99 offset:96
	s_waitcnt lgkmcnt(1)
	v_mfma_f32_32x32x16_bf16 v[16:31], v[0:3], v[4:7], v[16:31]
	v_add_f32_e32 v0, v89, v12
	v_add_f32_e32 v4, v90, v0
	v_sub_f32_e32 v0, v15, v92
	v_exp_f32_e32 v91, v0
	v_sub_f32_e32 v0, v179, v92
	v_exp_f32_e32 v97, v0
	ds_read_b128 v[0:3], v99 offset:16992
	s_waitcnt lgkmcnt(0)
	v_mfma_f32_32x32x16_bf16 v[16:31], v[0:3], v[8:11], v[16:31]
	v_sub_f32_e32 v0, v175, v92
	v_add_f32_e32 v4, v91, v4
	v_mfma_f32_32x32x16_bf16 v[32:47], v[84:87], v[8:11], v[32:47]
	v_exp_f32_e32 v85, v0
	v_sub_f32_e32 v0, v176, v92
	v_exp_f32_e32 v86, v0
	v_sub_f32_e32 v0, v178, v92
	v_add_f32_e32 v84, v97, v4
	v_cvt_pk_bf16_f32 v4, v194, v195
	v_cvt_pk_bf16_f32 v5, v196, v197
	v_cvt_pk_bf16_f32 v6, v198, v199
	v_cvt_pk_bf16_f32 v7, v200, v201
	ds_read_b128 v[12:15], v99 offset:128
	v_exp_f32_e32 v87, v0
	ds_read_b128 v[0:3], v99 offset:17024
	v_sub_f32_e32 v8, v177, v92
	v_exp_f32_e32 v122, v8
	s_waitcnt lgkmcnt(0)
	v_mfma_f32_32x32x16_bf16 v[16:31], v[0:3], v[4:7], v[16:31]
	v_add_f32_e32 v0, v85, v84
	v_add_f32_e32 v0, v86, v0
	v_add_f32_e32 v0, v87, v0
	v_add_f32_e32 v84, v122, v0
	v_sub_f32_e32 v0, v174, v92
	v_cvt_pk_bf16_f32 v8, v202, v203
	v_cvt_pk_bf16_f32 v9, v204, v205
	v_mfma_f32_32x32x16_bf16 v[32:47], v[12:15], v[4:7], v[32:47]
	v_cvt_pk_bf16_f32 v10, v206, v207
	v_cvt_pk_bf16_f32 v11, v208, v209
	ds_read_b128 v[12:15], v99 offset:160
	v_exp_f32_e32 v124, v0
	ds_read_b128 v[0:3], v99 offset:17056
	v_sub_f32_e32 v4, v173, v92
	v_exp_f32_e32 v126, v4
	s_waitcnt lgkmcnt(0)
	v_mfma_f32_32x32x16_bf16 v[16:31], v[0:3], v[8:11], v[16:31]
	v_add_f32_e32 v0, v124, v84
	v_add_f32_e32 v84, v126, v0
	v_sub_f32_e32 v0, v158, v92
	v_cvt_pk_bf16_f32 v4, v210, v211
	v_cvt_pk_bf16_f32 v5, v212, v213
	v_cvt_pk_bf16_f32 v6, v214, v215
	v_cvt_pk_bf16_f32 v7, v216, v93
	v_exp_f32_e32 v93, v0
	v_sub_f32_e32 v0, v172, v92
	v_mfma_f32_32x32x16_bf16 v[32:47], v[12:15], v[8:11], v[32:47]
	ds_read_b128 v[12:15], v99 offset:192
	v_exp_f32_e32 v128, v0
	ds_read_b128 v[0:3], v99 offset:17088
	v_sub_f32_e32 v8, v159, v92
	v_exp_f32_e32 v132, v8
	v_cvt_pk_bf16_f32 v8, v217, v94
	v_cvt_pk_bf16_f32 v9, v95, v96
	s_waitcnt lgkmcnt(0)
	v_mfma_f32_32x32x16_bf16 v[16:31], v[0:3], v[4:7], v[16:31]
	v_sub_f32_e32 v0, v157, v92
	v_cvt_pk_bf16_f32 v10, v88, v89
	v_exp_f32_e32 v88, v0
	v_add_f32_e32 v0, v93, v84
	v_add_f32_e32 v0, v128, v0
	v_add_f32_e32 v0, v132, v0
	v_cvt_pk_bf16_f32 v11, v90, v91
	v_mfma_f32_32x32x16_bf16 v[32:47], v[12:15], v[4:7], v[32:47]
	ds_read_b128 v[12:15], v99 offset:224
	v_add_f32_e32 v84, v88, v0
	ds_read_b128 v[0:3], v99 offset:17120
	v_sub_f32_e32 v4, v156, v92
	v_exp_f32_e32 v89, v4
	v_cvt_pk_bf16_f32 v4, v97, v85
	v_cvt_pk_bf16_f32 v5, v86, v87
	s_waitcnt lgkmcnt(0)
	v_mfma_f32_32x32x16_bf16 v[16:31], v[0:3], v[8:11], v[16:31]
	v_sub_f32_e32 v0, v105, v92
	v_exp_f32_e32 v85, v0
	v_sub_f32_e32 v0, v153, v92
	v_exp_f32_e32 v86, v0
	v_sub_f32_e32 v0, v155, v92
	v_cvt_pk_bf16_f32 v6, v122, v124
	v_cvt_pk_bf16_f32 v7, v126, v93
	v_mfma_f32_32x32x16_bf16 v[32:47], v[12:15], v[8:11], v[32:47]
	ds_read_b128 v[12:15], v99 offset:256
	v_exp_f32_e32 v87, v0
	ds_read_b128 v[0:3], v99 offset:17152
	v_sub_f32_e32 v8, v154, v92
	v_exp_f32_e32 v90, v8
	v_cvt_pk_bf16_f32 v8, v128, v132
	v_cvt_pk_bf16_f32 v9, v88, v89
	s_waitcnt lgkmcnt(0)
	v_mfma_f32_32x32x16_bf16 v[16:31], v[0:3], v[4:7], v[16:31]
	v_add_f32_e32 v0, v89, v84
	v_add_f32_e32 v0, v85, v0
	v_cvt_pk_bf16_f32 v10, v85, v86
	v_cvt_pk_bf16_f32 v11, v87, v90
	v_add_f32_e32 v0, v86, v0
	v_add_f32_e32 v0, v87, v0
	v_mfma_f32_32x32x16_bf16 v[32:47], v[12:15], v[4:7], v[32:47]
	ds_read_b128 v[12:15], v99 offset:288
	v_add_f32_e32 v4, v90, v0
	ds_read_b128 v[0:3], v99 offset:17184
	ds_bpermute_b32 v5, v82, v4
	v_sub_f32_e32 v6, v83, v92
	v_exp_f32_e32 v6, v6
	s_waitcnt vmcnt(3)
	ds_write_b128 v138, v[64:67]
	s_waitcnt vmcnt(2)
	ds_write_b128 v138, v[68:71] offset:1152
	s_waitcnt vmcnt(1)
	ds_write_b128 v138, v[72:75] offset:2304
	s_waitcnt vmcnt(0)
	ds_write_b128 v138, v[76:79] offset:3456
	s_waitcnt lgkmcnt(6)
	v_mfma_f32_32x32x16_bf16 v[32:47], v[12:15], v[8:11], v[32:47]
	s_waitcnt lgkmcnt(4)
; #define LAS __attribute__((address_space(3)))
; __device__ __forceinline__ unsigned pk2(float lo, float hi) { return pg8::cvt_pk_bf16(lo, hi); }
; __device__ __forceinline__ float bflo(unsigned w) { return __uint_as_float(w << 16); }
; __device__ __forceinline__ float bfhi(unsigned w) { return __uint_as_float(w & 0xffff0000u); }
; __device__ __forceinline__ float silu(float g) { return g * __builtin_amdgcn_rcpf(1.0f + __builtin_amdgcn_exp2f(-1.4426950408889634f * g)); }
; __device__ __forceinline__ void attn_unit(LAS unsigned char* lds, int unit, int mode, const bf16* QKVG, const float* sinks, const float* gain_a, bf16* MIX, float* SSA) {
;     ...
;         float ss = 0.f;
; #pragma unroll
;         for (int k = 0; k < 4; ++k) *(LAS v4u*)(wt_row + 8 * k * KP) = grow[k];
; #pragma unroll
;         for (int e = 0; e < 8; ++e) gt[e] = *(const LAS v2u*)(wt_frd + 32 * (e >> 2) + 8 * (e & 3));
; #pragma unroll
;         for (int e = 0; e < 8; ++e) {
;             const int db = e >> 2, g4 = e & 3;
;             const float o0 = ot[db][4 * g4 + 0] * inv, o1 = ot[db][4 * g4 + 1] * inv, o2 = ot[db][4 * g4 + 2] * inv, o3 = ot[db][4 * g4 + 3] * inv;
;             ss += (o0 * o0 + o1 * o1) + (o2 * o2 + o3 * o3);
;             const f32x4 gn = *(const LAS f32x4*)(GN + 4 * hh + 32 * db + 8 * g4);
;             v2u z; z.x = pk2(o0 * gn[0] * silu(bflo(gt[e].x)), o1 * gn[1] * silu(bfhi(gt[e].x)));
;             z.y = pk2(o2 * gn[2] * silu(bflo(gt[e].y)), o3 * gn[3] * silu(bfhi(gt[e].y)));
;             *(LAS v2u*)(wt_frd + 32 * db + 8 * g4) = z;
;         }
	v_add_f32_e32 v4, v4, v5
	v_add_f32_e32 v4, v6, v4
	v_rcp_f32_e32 v83, v4
	s_nop 7
	v_mul_f32_e32 v5, v32, v83
	v_mfma_f32_32x32x16_bf16 v[16:31], v[0:3], v[8:11], v[16:31]
	ds_read2_b64 v[6:9], v148 offset1:2
	ds_read2_b64 v[10:13], v148 offset0:4 offset1:6
	ds_read2_b64 v[64:67], v148 offset0:8 offset1:10
	ds_read2_b64 v[0:3], v148 offset0:12 offset1:14
	v_mul_f32_e32 v15, v33, v83
	s_waitcnt lgkmcnt(3)
	v_lshlrev_b32_e32 v4, 16, v6
	v_mul_f32_e32 v14, 0xbfb8aa3b, v4
	v_exp_f32_e32 v68, v14
	v_and_b32_e32 v14, 0xffff0000, v6
	v_mul_f32_e32 v6, 0xbfb8aa3b, v14
	v_mul_f32_e32 v69, v34, v83
	v_mul_f32_e32 v71, v35, v83
	ds_read_b128 v[32:35], v144
	v_exp_f32_e32 v6, v6
	v_add_f32_e32 v68, 1.0, v68
	v_rcp_f32_e32 v72, v68
	v_lshlrev_b32_e32 v68, 16, v7
	v_add_f32_e32 v6, 1.0, v6
	s_waitcnt lgkmcnt(0)
	v_mov_b32_e32 v73, v32
	v_rcp_f32_e32 v32, v6
	v_mul_f32_e32 v6, 0xbfb8aa3b, v68
	v_and_b32_e32 v70, 0xffff0000, v7
	v_mul_f32_e32 v74, v15, v15
	v_pk_mul_f32 v[14:15], v[32:33], v[14:15]
	v_exp_f32_e32 v6, v6
	v_mul_f32_e32 v7, 0xbfb8aa3b, v70
	v_mul_f32_e32 v14, v14, v15
	v_exp_f32_e32 v15, v7
	v_add_f32_e32 v6, 1.0, v6
	v_rcp_f32_e32 v6, v6
	v_mov_b32_e32 v7, v34
	v_add_f32_e32 v15, 1.0, v15
	v_rcp_f32_e32 v34, v15
	v_pk_mul_f32 v[72:73], v[72:73], v[4:5]
	v_pk_mul_f32 v[6:7], v[6:7], v[68:69]
	v_mul_f32_e32 v4, v72, v73
	v_cvt_pk_bf16_f32 v14, v4, v14
	v_mul_f32_e32 v4, v6, v7
	v_pk_mul_f32 v[6:7], v[34:35], v[70:71]
	v_mul_f32_e32 v75, v71, v71
	v_mul_f32_e32 v6, v6, v7
	v_cvt_pk_bf16_f32 v15, v4, v6
	v_lshlrev_b32_e32 v6, 16, v8
	ds_write_b64 v148, v[14:15]
	v_mul_f32_e32 v14, 0xbfb8aa3b, v6
	v_mul_f32_e32 v15, v37, v83
	v_mul_f32_e32 v37, v38, v83
	v_exp_f32_e32 v38, v14
	v_and_b32_e32 v14, 0xffff0000, v8
	v_mul_f32_e32 v8, 0xbfb8aa3b, v14
	ds_read_b128 v[32:35], v144 offset:32
	v_exp_f32_e32 v8, v8
	v_add_f32_e32 v38, 1.0, v38
	v_rcp_f32_e32 v68, v38
	v_fmac_f32_e32 v75, v69, v69
	v_add_f32_e32 v8, 1.0, v8
	s_waitcnt lgkmcnt(0)
	v_mov_b32_e32 v69, v32
	v_rcp_f32_e32 v32, v8
	v_mul_f32_e32 v39, v39, v83
	v_mul_f32_e32 v7, v36, v83
	v_mul_f32_e32 v4, v15, v15
	v_mul_f32_e32 v36, v39, v39
	v_fmac_f32_e32 v4, v7, v7
	v_fmac_f32_e32 v36, v37, v37
	v_pk_mul_f32 v[6:7], v[68:69], v[6:7]
	v_add_f32_e32 v4, v4, v36
	v_mul_f32_e32 v8, v6, v7
	v_pk_mul_f32 v[6:7], v[32:33], v[14:15]
	v_lshlrev_b32_e32 v36, 16, v9
	v_mul_f32_e32 v14, v6, v7
	v_mul_f32_e32 v6, 0xbfb8aa3b, v36
	v_and_b32_e32 v38, 0xffff0000, v9
	v_exp_f32_e32 v6, v6
	v_mul_f32_e32 v7, 0xbfb8aa3b, v38
	v_exp_f32_e32 v9, v7
	v_mov_b32_e32 v7, v34
	v_add_f32_e32 v6, 1.0, v6
	v_rcp_f32_e32 v6, v6
	v_add_f32_e32 v9, 1.0, v9
	v_rcp_f32_e32 v34, v9
	v_cvt_pk_bf16_f32 v8, v8, v14
	v_pk_mul_f32 v[6:7], v[6:7], v[36:37]
	v_lshlrev_b32_e32 v14, 16, v10
	v_mul_f32_e32 v9, v6, v7
	v_pk_mul_f32 v[6:7], v[34:35], v[38:39]
	v_mul_f32_e32 v32, 0xbfb8aa3b, v14
	v_mul_f32_e32 v6, v6, v7
	v_cvt_pk_bf16_f32 v9, v9, v6
	ds_write_b64 v148, v[8:9] offset:16
	v_exp_f32_e32 v38, v32
	v_and_b32_e32 v32, 0xffff0000, v10
	ds_read_b128 v[6:9], v144 offset:64
	v_mul_f32_e32 v10, 0xbfb8aa3b, v32
	v_exp_f32_e32 v10, v10
	v_add_f32_e32 v38, 1.0, v38
	v_rcp_f32_e32 v38, v38
	s_waitcnt lgkmcnt(0)
	v_mov_b32_e32 v39, v6
	v_add_f32_e32 v6, 1.0, v10
	v_rcp_f32_e32 v6, v6
	v_mul_f32_e32 v33, v41, v83
	v_mul_f32_e32 v37, v43, v83
	v_mul_f32_e32 v15, v40, v83
	v_mul_f32_e32 v35, v42, v83
	v_mul_f32_e32 v34, v33, v33
	v_mul_f32_e32 v36, v37, v37
	v_fmac_f32_e32 v34, v15, v15
	v_fmac_f32_e32 v36, v35, v35
	v_add_f32_e32 v40, v34, v36
	v_pk_mul_f32 v[14:15], v[38:39], v[14:15]
	v_pk_mul_f32 v[6:7], v[6:7], v[32:33]
	v_lshlrev_b32_e32 v34, 16, v11
	v_mul_f32_e32 v10, v14, v15
	v_mul_f32_e32 v14, v6, v7
	v_mul_f32_e32 v6, 0xbfb8aa3b, v34
	v_and_b32_e32 v36, 0xffff0000, v11
	v_exp_f32_e32 v6, v6
	v_mul_f32_e32 v7, 0xbfb8aa3b, v36
	v_exp_f32_e32 v11, v7
	v_mov_b32_e32 v7, v8
	v_add_f32_e32 v6, 1.0, v6
	v_rcp_f32_e32 v6, v6
	v_add_f32_e32 v8, 1.0, v11
	v_rcp_f32_e32 v8, v8
	v_cvt_pk_bf16_f32 v10, v10, v14
	v_pk_mul_f32 v[6:7], v[6:7], v[34:35]
	v_mul_f32_e32 v15, v45, v83
	v_mul_f32_e32 v11, v6, v7
	v_pk_mul_f32 v[6:7], v[8:9], v[36:37]
	v_mul_f32_e32 v35, v47, v83
	v_mul_f32_e32 v6, v6, v7
	v_cvt_pk_bf16_f32 v11, v11, v6
	ds_write_b64 v148, v[10:11] offset:32
	v_lshlrev_b32_e32 v10, 16, v12
	v_mul_f32_e32 v14, 0xbfb8aa3b, v10
	v_exp_f32_e32 v36, v14
	v_and_b32_e32 v14, 0xffff0000, v12
	ds_read_b128 v[6:9], v144 offset:96
	v_mul_f32_e32 v12, 0xbfb8aa3b, v14
	v_exp_f32_e32 v12, v12
	v_add_f32_e32 v36, 1.0, v36
	v_rcp_f32_e32 v36, v36
	s_waitcnt lgkmcnt(0)
	v_mov_b32_e32 v37, v6
	v_add_f32_e32 v6, 1.0, v12
	v_rcp_f32_e32 v6, v6
	v_mul_f32_e32 v11, v44, v83
	v_mul_f32_e32 v33, v46, v83
	v_mul_f32_e32 v32, v15, v15
	v_mul_f32_e32 v34, v35, v35
	v_fmac_f32_e32 v32, v11, v11
	v_fmac_f32_e32 v34, v33, v33
	v_add_f32_e32 v38, v32, v34
	v_pk_mul_f32 v[10:11], v[36:37], v[10:11]
	v_pk_mul_f32 v[6:7], v[6:7], v[14:15]
	v_lshlrev_b32_e32 v32, 16, v13
	v_mul_f32_e32 v10, v10, v11
	v_mul_f32_e32 v11, v6, v7
	v_mul_f32_e32 v6, 0xbfb8aa3b, v32
	v_and_b32_e32 v34, 0xffff0000, v13
	v_exp_f32_e32 v6, v6
	v_mul_f32_e32 v7, 0xbfb8aa3b, v34
	v_exp_f32_e32 v12, v7
	v_mov_b32_e32 v7, v8
	v_add_f32_e32 v6, 1.0, v6
	v_rcp_f32_e32 v6, v6
	v_add_f32_e32 v8, 1.0, v12
	v_rcp_f32_e32 v8, v8
	v_cvt_pk_bf16_f32 v10, v10, v11
	v_pk_mul_f32 v[6:7], v[6:7], v[32:33]
	v_mul_f32_e32 v15, v18, v83
	v_mul_f32_e32 v11, v6, v7
	v_pk_mul_f32 v[6:7], v[8:9], v[34:35]
	v_mul_f32_e32 v13, v17, v83
	v_mul_f32_e32 v6, v6, v7
	v_cvt_pk_bf16_f32 v11, v11, v6
	ds_write_b64 v148, v[10:11] offset:48
	v_lshlrev_b32_e32 v10, 16, v64
	v_mul_f32_e32 v12, 0xbfb8aa3b, v10
	v_exp_f32_e32 v18, v12
	v_and_b32_e32 v12, 0xffff0000, v64
	v_mul_f32_e32 v17, v19, v83
	ds_read_b128 v[6:9], v144 offset:128
	v_mul_f32_e32 v19, 0xbfb8aa3b, v12
	v_exp_f32_e32 v32, v19
	v_add_f32_e32 v18, 1.0, v18
	v_rcp_f32_e32 v18, v18
	s_waitcnt lgkmcnt(0)
; #define LAS __attribute__((address_space(3)))
; __device__ __forceinline__ unsigned pk2(float lo, float hi) { return pg8::cvt_pk_bf16(lo, hi); }
; __device__ __forceinline__ float bflo(unsigned w) { return __uint_as_float(w << 16); }
; __device__ __forceinline__ float bfhi(unsigned w) { return __uint_as_float(w & 0xffff0000u); }
; __device__ __forceinline__ float silu(float g) { return g * __builtin_amdgcn_rcpf(1.0f + __builtin_amdgcn_exp2f(-1.4426950408889634f * g)); }
; __device__ __forceinline__ void attn_unit(LAS unsigned char* lds, int unit, int mode, const bf16* QKVG, const float* sinks, const float* gain_a, bf16* MIX, float* SSA) {
;     ...
;         for (int e = 0; e < 8; ++e) gt[e] = *(const LAS v2u*)(wt_frd + 32 * (e >> 2) + 8 * (e & 3));
; #pragma unroll
;         for (int e = 0; e < 8; ++e) {
;             const int db = e >> 2, g4 = e & 3;
;             const float o0 = ot[db][4 * g4 + 0] * inv, o1 = ot[db][4 * g4 + 1] * inv, o2 = ot[db][4 * g4 + 2] * inv, o3 = ot[db][4 * g4 + 3] * inv;
;             ss += (o0 * o0 + o1 * o1) + (o2 * o2 + o3 * o3);
;             const f32x4 gn = *(const LAS f32x4*)(GN + 4 * hh + 32 * db + 8 * g4);
;             v2u z; z.x = pk2(o0 * gn[0] * silu(bflo(gt[e].x)), o1 * gn[1] * silu(bfhi(gt[e].x)));
;             z.y = pk2(o2 * gn[2] * silu(bflo(gt[e].y)), o3 * gn[3] * silu(bfhi(gt[e].y)));
;             *(LAS v2u*)(wt_frd + 32 * db + 8 * g4) = z;
;         }
;         {
;             bf16* orow0 = MIX + (size_t)(T0 + 32 * i + r8) * DMIX + 1024 + h * 64 + 8 * c8;
; #pragma unroll
;             for (int k = 0; k < 4; ++k) { const v4u v = *(const LAS v4u*)(wt_row + 8 * k * KP); *(v4u*)(orow0 + (size_t)(8 * k) * DMIX) = v; }
;         }
; #pragma unroll
;         for (int k = 0; k < 4; ++k) *(LAS v4u*)(wt_row + 8 * k * KP) = qrow[k];
;         ss += __shfl_xor(ss, 32);
;         if (hh == 0) SS[w * 128 + 32 * i + q] = ss;
	v_mov_b32_e32 v19, v6
	v_add_f32_e32 v6, 1.0, v32
	v_rcp_f32_e32 v6, v6
	v_mul_f32_e32 v11, v16, v83
	v_mul_f32_e32 v14, v13, v13
	v_mul_f32_e32 v16, v17, v17
	v_fmac_f32_e32 v14, v11, v11
	v_fmac_f32_e32 v16, v15, v15
	v_add_f32_e32 v32, v14, v16
	v_pk_mul_f32 v[10:11], v[18:19], v[10:11]
	v_pk_mul_f32 v[6:7], v[6:7], v[12:13]
	v_lshlrev_b32_e32 v14, 16, v65
	v_mul_f32_e32 v10, v10, v11
	v_mul_f32_e32 v11, v6, v7
	v_mul_f32_e32 v6, 0xbfb8aa3b, v14
	v_and_b32_e32 v16, 0xffff0000, v65
	v_exp_f32_e32 v6, v6
	v_mul_f32_e32 v7, 0xbfb8aa3b, v16
	v_exp_f32_e32 v12, v7
	v_mov_b32_e32 v7, v8
	v_add_f32_e32 v6, 1.0, v6
	v_rcp_f32_e32 v6, v6
	v_add_f32_e32 v8, 1.0, v12
	v_rcp_f32_e32 v8, v8
	v_cvt_pk_bf16_f32 v10, v10, v11
	v_pk_mul_f32 v[6:7], v[6:7], v[14:15]
	v_mul_f32_e32 v13, v21, v83
	v_mul_f32_e32 v11, v6, v7
	v_pk_mul_f32 v[6:7], v[8:9], v[16:17]
	v_mul_f32_e32 v17, v23, v83
	v_mul_f32_e32 v6, v6, v7
	v_cvt_pk_bf16_f32 v11, v11, v6
	ds_write_b64 v148, v[10:11] offset:64
	v_lshlrev_b32_e32 v10, 16, v66
	v_mul_f32_e32 v12, 0xbfb8aa3b, v10
	v_exp_f32_e32 v18, v12
	v_and_b32_e32 v12, 0xffff0000, v66
	ds_read_b128 v[6:9], v144 offset:160
	v_mul_f32_e32 v19, 0xbfb8aa3b, v12
	v_mul_f32_e32 v11, v20, v83
	v_exp_f32_e32 v20, v19
	v_add_f32_e32 v18, 1.0, v18
	s_waitcnt lgkmcnt(0)
	v_mov_b32_e32 v19, v6
	v_rcp_f32_e32 v18, v18
	v_add_f32_e32 v6, 1.0, v20
	v_rcp_f32_e32 v6, v6
	v_mul_f32_e32 v15, v22, v83
	v_mul_f32_e32 v14, v13, v13
	v_mul_f32_e32 v16, v17, v17
	v_fmac_f32_e32 v14, v11, v11
	v_fmac_f32_e32 v16, v15, v15
	v_add_f32_e32 v20, v14, v16
	v_pk_mul_f32 v[10:11], v[18:19], v[10:11]
	v_pk_mul_f32 v[6:7], v[6:7], v[12:13]
	v_lshlrev_b32_e32 v14, 16, v67
	v_mul_f32_e32 v10, v10, v11
	v_mul_f32_e32 v11, v6, v7
	v_mul_f32_e32 v6, 0xbfb8aa3b, v14
	v_and_b32_e32 v16, 0xffff0000, v67
	v_exp_f32_e32 v6, v6
	v_mul_f32_e32 v7, 0xbfb8aa3b, v16
	v_exp_f32_e32 v12, v7
	v_mov_b32_e32 v7, v8
	v_add_f32_e32 v6, 1.0, v6
	v_rcp_f32_e32 v6, v6
	v_add_f32_e32 v8, 1.0, v12
	v_rcp_f32_e32 v8, v8
	v_cvt_pk_bf16_f32 v10, v10, v11
	v_pk_mul_f32 v[6:7], v[6:7], v[14:15]
	v_mul_f32_e32 v13, v25, v83
	v_mul_f32_e32 v11, v6, v7
	v_pk_mul_f32 v[6:7], v[8:9], v[16:17]
	v_mul_f32_e32 v17, v27, v83
	v_mul_f32_e32 v6, v6, v7
	v_cvt_pk_bf16_f32 v11, v11, v6
	ds_write_b64 v148, v[10:11] offset:80
	v_lshlrev_b32_e32 v10, 16, v0
	v_mul_f32_e32 v12, 0xbfb8aa3b, v10
	v_exp_f32_e32 v18, v12
	v_and_b32_e32 v12, 0xffff0000, v0
	v_mul_f32_e32 v0, 0xbfb8aa3b, v12
	ds_read_b128 v[6:9], v144 offset:192
	v_exp_f32_e32 v0, v0
	v_mul_f32_e32 v11, v24, v83
	v_mul_f32_e32 v15, v26, v83
	v_mul_f32_e32 v14, v13, v13
	v_add_f32_e32 v0, 1.0, v0
	v_mul_f32_e32 v16, v17, v17
	s_waitcnt lgkmcnt(0)
	v_mov_b32_e32 v19, v6
	v_rcp_f32_e32 v6, v0
	v_fmac_f32_e32 v14, v11, v11
	v_fmac_f32_e32 v16, v15, v15
	v_add_f32_e32 v21, v14, v16
	v_lshlrev_b32_e32 v14, 16, v1
	v_mul_f32_e32 v0, 0xbfb8aa3b, v14
	v_and_b32_e32 v16, 0xffff0000, v1
	v_pk_mul_f32 v[6:7], v[6:7], v[12:13]
	v_exp_f32_e32 v0, v0
	v_mul_f32_e32 v1, 0xbfb8aa3b, v16
	v_mul_f32_e32 v6, v6, v7
	v_exp_f32_e32 v7, v1
	v_add_f32_e32 v0, 1.0, v0
	v_rcp_f32_e32 v0, v0
	v_add_f32_e32 v18, 1.0, v18
	v_add_f32_e32 v7, 1.0, v7
	v_mov_b32_e32 v1, v8
	v_rcp_f32_e32 v8, v7
	v_rcp_f32_e32 v18, v18
	v_pk_mul_f32 v[0:1], v[0:1], v[14:15]
	v_and_b32_e32 v14, 0xffff0000, v3
	v_mul_f32_e32 v7, v0, v1
	v_pk_mul_f32 v[0:1], v[8:9], v[16:17]
	v_pk_mul_f32 v[10:11], v[18:19], v[10:11]
	v_mul_f32_e32 v0, v0, v1
	v_mul_f32_e32 v10, v10, v11
	v_cvt_pk_bf16_f32 v6, v10, v6
	v_cvt_pk_bf16_f32 v7, v7, v0
	v_lshlrev_b32_e32 v0, 16, v2
	v_mul_f32_e32 v10, 0xbfb8aa3b, v0
	v_exp_f32_e32 v12, v10
	v_and_b32_e32 v10, 0xffff0000, v2
	ds_write_b64 v148, v[6:7] offset:96
	v_mul_f32_e32 v2, 0xbfb8aa3b, v10
	ds_read_b128 v[6:9], v144 offset:224
	v_exp_f32_e32 v2, v2
	v_add_f32_e32 v12, 1.0, v12
	v_rcp_f32_e32 v16, v12
	v_mul_f32_e32 v11, v29, v83
	v_add_f32_e32 v2, 1.0, v2
	s_waitcnt lgkmcnt(0)
	v_mov_b32_e32 v17, v6
	v_rcp_f32_e32 v6, v2
	v_mul_f32_e32 v1, v28, v83
	v_mul_f32_e32 v18, v11, v11
	v_fmac_f32_e32 v18, v1, v1
	v_pk_mul_f32 v[0:1], v[16:17], v[0:1]
	v_lshlrev_b32_e32 v12, 16, v3
	v_mul_f32_e32 v2, v0, v1
	v_pk_mul_f32 v[0:1], v[6:7], v[10:11]
	v_mul_f32_e32 v13, v30, v83
	v_mul_f32_e32 v6, v0, v1
	v_mul_f32_e32 v0, 0xbfb8aa3b, v12
	v_exp_f32_e32 v0, v0
	v_mul_f32_e32 v1, 0xbfb8aa3b, v14
	v_exp_f32_e32 v3, v1
	v_mov_b32_e32 v1, v8
	v_add_f32_e32 v0, 1.0, v0
	v_rcp_f32_e32 v0, v0
	v_add_f32_e32 v3, 1.0, v3
	v_rcp_f32_e32 v8, v3
	v_mul_f32_e32 v15, v31, v83
	v_pk_mul_f32 v[0:1], v[0:1], v[12:13]
	v_mul_f32_e32 v19, v15, v15
	v_mul_f32_e32 v3, v0, v1
	v_pk_mul_f32 v[0:1], v[8:9], v[14:15]
	v_cvt_pk_bf16_f32 v2, v2, v6
	v_fmac_f32_e32 v19, v13, v13
	v_mul_f32_e32 v0, v0, v1
	v_cvt_pk_bf16_f32 v3, v3, v0
	ds_write_b64 v148, v[2:3] offset:112
	ds_read_b128 v[0:3], v138
	ds_read_b128 v[6:9], v138 offset:1152
	ds_read_b128 v[10:13], v138 offset:2304
	ds_read_b128 v[14:17], v138 offset:3456
	v_fmac_f32_e32 v74, v5, v5
	s_waitcnt lgkmcnt(3)
	global_store_dwordx4 v[114:115], v[0:3], off offset:2048
	s_waitcnt lgkmcnt(2)
	global_store_dwordx4 v[116:117], v[6:9], off offset:2048
	s_waitcnt lgkmcnt(1)
	global_store_dwordx4 v[118:119], v[10:13], off offset:2048
	s_waitcnt lgkmcnt(0)
	global_store_dwordx4 v[120:121], v[14:17], off offset:2048
	v_add_f32_e32 v0, v74, v75
	v_add_f32_e32 v0, v0, v4
	v_add_f32_e32 v0, v40, v0
	v_add_f32_e32 v0, v38, v0
	v_add_f32_e32 v0, v32, v0
	v_add_f32_e32 v0, v20, v0
	v_add_f32_e32 v18, v18, v19
	v_add_f32_e32 v0, v21, v0
	v_add_f32_e32 v0, v18, v0
	ds_bpermute_b32 v1, v82, v0
	ds_write_b128 v138, v[48:51]
	ds_write_b128 v138, v[52:55] offset:1152
	ds_write_b128 v138, v[56:59] offset:2304
	ds_write_b128 v138, v[60:63] offset:3456
	s_and_saveexec_b64 s[6:7], s[4:5]
	s_cbranch_execz .LBB0_295
	s_waitcnt lgkmcnt(4)
	v_add_f32_e32 v0, v0, v1
	ds_write_b32 v146, v0
	s_branch .LBB0_295
